# LN1 row loop: counted vmcnt ladder re-derived for the back edge (no longer waits for the previous row's stores before consuming the prefetched row)
# baseline (speedup 1.0000x reference)
.LBB0_930:
	s_waitcnt vmcnt(16)
	v_lshlrev_b32_e32 v42, 16, v2
	v_and_b32_e32 v43, 0xffff0000, v2
	v_lshlrev_b32_e32 v44, 16, v3
	v_and_b32_e32 v45, 0xffff0000, v3
	s_waitcnt vmcnt(12)
	v_lshlrev_b32_e32 v46, 16, v4
	v_and_b32_e32 v47, 0xffff0000, v4
	v_lshlrev_b32_e32 v48, 16, v5
	v_and_b32_e32 v49, 0xffff0000, v5
	v_pk_add_f32 v[42:43], v[42:43], v[46:47]
	v_pk_add_f32 v[44:45], v[44:45], v[48:49]
	s_waitcnt vmcnt(12)
	v_lshlrev_b32_e32 v46, 16, v0
	v_and_b32_e32 v47, 0xffff0000, v0
	v_lshlrev_b32_e32 v48, 16, v1
	v_and_b32_e32 v49, 0xffff0000, v1
	v_pk_add_f32 v[50:51], v[46:47], 0 op_sel_hi:[1,0]
	v_pk_add_f32 v[46:47], v[48:49], 0 op_sel_hi:[1,0]
	v_pk_fma_f32 v[48:49], v[42:43], s[80:81], v[50:51] op_sel_hi:[1,0,1]
	v_pk_fma_f32 v[46:47], v[44:45], s[80:81], v[46:47] op_sel_hi:[1,0,1]
	s_waitcnt vmcnt(12)
	v_lshlrev_b32_e32 v42, 16, v8
	v_and_b32_e32 v43, 0xffff0000, v8
	v_lshlrev_b32_e32 v44, 16, v9
	v_and_b32_e32 v45, 0xffff0000, v9
	s_waitcnt vmcnt(11)
	v_lshlrev_b32_e32 v50, 16, v10
	v_and_b32_e32 v51, 0xffff0000, v10
	v_lshlrev_b32_e32 v52, 16, v11
	v_and_b32_e32 v53, 0xffff0000, v11
	v_pk_add_f32 v[42:43], v[42:43], v[50:51]
	v_pk_add_f32 v[44:45], v[44:45], v[52:53]
	s_waitcnt vmcnt(11)
	v_lshlrev_b32_e32 v50, 16, v6
	v_and_b32_e32 v51, 0xffff0000, v6
	v_lshlrev_b32_e32 v52, 16, v7
	v_and_b32_e32 v53, 0xffff0000, v7
	v_pk_add_f32 v[50:51], v[50:51], 0 op_sel_hi:[1,0]
	v_pk_add_f32 v[52:53], v[52:53], 0 op_sel_hi:[1,0]
	s_waitcnt vmcnt(9)
	v_lshlrev_b32_e32 v54, 16, v17
	v_pk_fma_f32 v[58:59], v[44:45], s[80:81], v[52:53] op_sel_hi:[1,0,1]
	v_pk_fma_f32 v[52:53], v[42:43], s[80:81], v[50:51] op_sel_hi:[1,0,1]
	v_lshlrev_b32_e32 v42, 16, v12
	v_and_b32_e32 v43, 0xffff0000, v12
	v_lshlrev_b32_e32 v44, 16, v13
	v_and_b32_e32 v45, 0xffff0000, v13
	v_lshlrev_b32_e32 v50, 16, v16
	v_and_b32_e32 v51, 0xffff0000, v16
	v_and_b32_e32 v55, 0xffff0000, v17
	v_pk_add_f32 v[42:43], v[42:43], v[50:51]
	v_pk_add_f32 v[44:45], v[44:45], v[54:55]
	v_lshlrev_b32_e32 v50, 16, v20
	v_and_b32_e32 v51, 0xffff0000, v20
	v_lshlrev_b32_e32 v54, 16, v21
	v_and_b32_e32 v55, 0xffff0000, v21
	v_pk_add_f32 v[50:51], v[50:51], 0 op_sel_hi:[1,0]
	v_pk_add_f32 v[54:55], v[54:55], 0 op_sel_hi:[1,0]
	v_pk_fma_f32 v[42:43], v[42:43], s[80:81], v[50:51] op_sel_hi:[1,0,1]
	v_pk_fma_f32 v[54:55], v[44:45], s[80:81], v[54:55] op_sel_hi:[1,0,1]
	v_lshlrev_b32_e32 v44, 16, v28
	v_and_b32_e32 v45, 0xffff0000, v28
	v_lshlrev_b32_e32 v50, 16, v29
	v_and_b32_e32 v51, 0xffff0000, v29
	v_lshlrev_b32_e32 v56, 16, v32
	v_and_b32_e32 v57, 0xffff0000, v32
	v_lshlrev_b32_e32 v62, 16, v33
	v_and_b32_e32 v63, 0xffff0000, v33
	v_pk_add_f32 v[56:57], v[44:45], v[56:57]
	v_pk_add_f32 v[44:45], v[50:51], v[62:63]
	s_waitcnt vmcnt(8)
	v_lshlrev_b32_e32 v50, 16, v40
	v_and_b32_e32 v51, 0xffff0000, v40
	v_lshlrev_b32_e32 v62, 16, v41
	v_and_b32_e32 v63, 0xffff0000, v41
	v_add_u32_e32 v60, s0, v72
	v_pk_add_f32 v[50:51], v[50:51], 0 op_sel_hi:[1,0]
	v_pk_add_f32 v[62:63], v[62:63], 0 op_sel_hi:[1,0]
	v_pk_fma_f32 v[50:51], v[56:57], s[80:81], v[50:51] op_sel_hi:[1,0,1]
	v_pk_fma_f32 v[44:45], v[44:45], s[80:81], v[62:63] op_sel_hi:[1,0,1]
	v_cmp_gt_i32_e32 vcc, s73, v60
	s_and_saveexec_b64 s[4:5], vcc
	s_xor_b64 s[4:5], exec, s[4:5]
	s_cbranch_execz .LBB0_932
	v_add_f32_e32 v56, v48, v49
	v_add_f32_e32 v57, v46, v56
	v_add_f32_e32 v56, v52, v53
	v_add_f32_e32 v56, v58, v56
	v_add_f32_e32 v65, v59, v56
	v_mul_f32_e32 v56, v53, v53
	v_pk_fma_f32 v[66:67], v[52:53], v[52:53], v[56:57] op_sel_hi:[1,1,0]
	v_mul_f32_e32 v56, v59, v59
	v_pk_fma_f32 v[66:67], v[58:59], v[58:59], v[66:67]
	v_pk_mul_f32 v[62:63], v[48:49], v[48:49]
	v_pk_add_f32 v[66:67], v[56:57], v[66:67] op_sel_hi:[0,1]
	v_add_f32_e32 v56, v42, v43
	v_add_f32_e32 v56, v54, v56
	v_add_f32_e32 v69, v55, v56
	v_mul_f32_e32 v56, v43, v43
	v_pk_fma_f32 v[70:71], v[42:43], v[42:43], v[56:57] op_sel_hi:[1,1,0]
	v_pk_mul_f32 v[60:61], v[46:47], v[46:47]
	v_fmac_f32_e32 v63, v48, v48
	v_pk_fma_f32 v[70:71], v[54:55], v[54:55], v[70:71]
	v_mul_f32_e32 v56, v55, v55
	v_add_f32_e32 v60, v60, v63
	v_mul_f32_e32 v62, v47, v47
	v_pk_add_f32 v[70:71], v[56:57], v[70:71] op_sel_hi:[0,1]
	v_mul_f32_e32 v80, v50, v50
	v_mul_f32_e32 v56, v51, v51
	v_mov_b32_e32 v63, v50
	v_mov_b32_e32 v61, v51
	v_mov_b32_e32 v81, v47
	v_mul_f32_e32 v64, v44, v44
	v_pk_add_f32 v[60:61], v[62:63], v[60:61]
	v_mov_b32_e32 v67, v44
	v_pk_add_f32 v[56:57], v[80:81], v[56:57]
	v_mul_f32_e32 v68, v45, v45
	v_pk_add_f32 v[60:61], v[66:67], v[60:61]
	v_mov_b32_e32 v71, v45
	v_pk_add_f32 v[56:57], v[64:65], v[56:57]
	v_pk_add_f32 v[60:61], v[70:71], v[60:61]
	v_pk_add_f32 v[56:57], v[68:69], v[56:57]
	s_nop 0
	v_pk_add_f32 v[56:57], v[60:61], v[56:57]
